# v68 with full vmcnt(0) drain before the scan's LDS restage (no load/store ordering assumption)
# baseline (speedup 1.0000x reference)
.Lscan_w1:
	v_pk_mul_f32 v[16:17], v[16:17], v[196:197] op_sel_hi:[1,0]
	v_pk_mul_f32 v[18:19], v[18:19], v[196:197] op_sel_hi:[1,0]
	s_waitcnt lgkmcnt(4)
	v_mfma_f32_16x16x32_bf16 v[176:179], v[224:227], v[132:135], 0
	ds_read_b128 v[216:219], v2 offset:25600
	v_pk_mul_f32 v[4:5], v[4:5], v[196:197] op_sel_hi:[1,0]
	v_pk_mul_f32 v[6:7], v[6:7], v[196:197] op_sel_hi:[1,0]
	s_waitcnt lgkmcnt(4)
	v_mfma_f32_16x16x32_bf16 v[180:183], v[228:231], v[132:135], 0
	ds_read_b128 v[220:223], v2 offset:29696
	v_pk_mul_f32 v[44:45], v[44:45], v[196:197] op_sel_hi:[1,0]
	v_pk_mul_f32 v[46:47], v[46:47], v[196:197] op_sel_hi:[1,0]
	v_lshlrev_b32_e32 v240, 16, v188
	v_and_b32_e32 v241, 0xffff0000, v188
	v_lshlrev_b32_e32 v242, 16, v189
	v_and_b32_e32 v243, 0xffff0000, v189
	s_waitcnt lgkmcnt(4)
	v_mfma_f32_16x16x32_bf16 v[184:187], v[232:235], v[132:135], 0
	ds_read_b128 v[224:227], v2 offset:18432
	v_pk_mul_f32 v[76:77], v[76:77], v[196:197] op_sel_hi:[1,0]
	v_pk_mul_f32 v[78:79], v[78:79], v[196:197] op_sel_hi:[1,0]
	v_sub_f32_e32 v156, v240, v156
	v_sub_f32_e32 v157, v241, v157
	v_sub_f32_e32 v158, v242, v158
	v_sub_f32_e32 v159, v243, v159
	s_waitcnt lgkmcnt(4)
	v_mfma_f32_16x16x32_bf16 v[172:175], v[236:239], v[136:139], v[172:175]
	ds_read_b128 v[228:231], v2 offset:22528
	v_pk_mul_f32 v[84:85], v[84:85], v[196:197] op_sel_hi:[1,0]
	v_pk_mul_f32 v[86:87], v[86:87], v[196:197] op_sel_hi:[1,0]
	v_lshlrev_b32_e32 v240, 16, v190
	v_and_b32_e32 v241, 0xffff0000, v190
	v_lshlrev_b32_e32 v242, 16, v191
	v_and_b32_e32 v243, 0xffff0000, v191
	s_waitcnt lgkmcnt(4)
	v_mfma_f32_16x16x32_bf16 v[176:179], v[212:215], v[136:139], v[176:179]
	ds_read_b128 v[232:235], v2 offset:26624
	v_pk_mul_f32 v[88:89], v[88:89], v[196:197] op_sel_hi:[1,0]
	v_pk_mul_f32 v[90:91], v[90:91], v[196:197] op_sel_hi:[1,0]
	v_sub_f32_e32 v160, v240, v160
	v_sub_f32_e32 v161, v241, v161
	v_sub_f32_e32 v162, v242, v162
	v_sub_f32_e32 v163, v243, v163
	s_waitcnt lgkmcnt(4)
	v_mfma_f32_16x16x32_bf16 v[180:183], v[216:219], v[136:139], v[180:183]
	ds_read_b128 v[236:239], v2 offset:30720
	v_pk_mul_f32 v[92:93], v[92:93], v[196:197] op_sel_hi:[1,0]
	v_pk_mul_f32 v[94:95], v[94:95], v[196:197] op_sel_hi:[1,0]
	v_lshlrev_b32_e32 v240, 16, v192
	v_and_b32_e32 v241, 0xffff0000, v192
	v_lshlrev_b32_e32 v242, 16, v193
	v_and_b32_e32 v243, 0xffff0000, v193
	v_cvt_pk_bf16_f32 v148, v156, v157
	v_cvt_pk_bf16_f32 v149, v158, v159
	v_cvt_pk_bf16_f32 v150, v160, v161
	v_cvt_pk_bf16_f32 v151, v162, v163
	s_waitcnt lgkmcnt(4)
	v_mfma_f32_16x16x32_bf16 v[184:187], v[220:223], v[136:139], v[184:187]
	ds_read_b128 v[212:215], v2 offset:19456
	v_pk_mul_f32 v[96:97], v[96:97], v[196:197] op_sel_hi:[1,0]
	v_pk_mul_f32 v[98:99], v[98:99], v[196:197] op_sel_hi:[1,0]
	v_sub_f32_e32 v164, v240, v164
	v_sub_f32_e32 v165, v241, v165
	v_sub_f32_e32 v166, v242, v166
	v_sub_f32_e32 v167, v243, v167
	s_waitcnt lgkmcnt(4)
	v_mfma_f32_16x16x32_bf16 v[172:175], v[224:227], v[140:143], v[172:175]
	ds_read_b128 v[216:219], v2 offset:23552
	v_lshlrev_b32_e32 v240, 16, v194
	v_and_b32_e32 v241, 0xffff0000, v194
	v_lshlrev_b32_e32 v242, 16, v195
	v_and_b32_e32 v243, 0xffff0000, v195
	s_waitcnt lgkmcnt(4)
	v_mfma_f32_16x16x32_bf16 v[176:179], v[228:231], v[140:143], v[176:179]
	ds_read_b128 v[220:223], v2 offset:27648
	v_sub_f32_e32 v168, v240, v168
	v_sub_f32_e32 v169, v241, v169
	v_sub_f32_e32 v170, v242, v170
	v_sub_f32_e32 v171, v243, v171
	s_waitcnt lgkmcnt(4)
	v_mfma_f32_16x16x32_bf16 v[180:183], v[232:235], v[140:143], v[180:183]
	ds_read_b128 v[224:227], v2 offset:31744
	v_cvt_pk_bf16_f32 v152, v164, v165
	v_cvt_pk_bf16_f32 v153, v166, v167
	v_cvt_pk_bf16_f32 v154, v168, v169
	v_cvt_pk_bf16_f32 v155, v170, v171
	s_waitcnt lgkmcnt(4)
	v_mfma_f32_16x16x32_bf16 v[184:187], v[236:239], v[140:143], v[184:187]
	ds_read_b128 v[228:231], v2 offset:49152
	s_waitcnt lgkmcnt(4)
	v_mfma_f32_16x16x32_bf16 v[172:175], v[212:215], v[144:147], v[172:175]
	ds_read_b128 v[232:235], v2 offset:51200
	s_waitcnt lgkmcnt(4)
	v_mfma_f32_16x16x32_bf16 v[176:179], v[216:219], v[144:147], v[176:179]
	ds_read_b128 v[236:239], v2 offset:53248
	s_waitcnt lgkmcnt(4)
	v_mfma_f32_16x16x32_bf16 v[180:183], v[220:223], v[144:147], v[180:183]
	ds_read_b128 v[212:215], v2 offset:55296
	s_waitcnt lgkmcnt(4)
	v_mfma_f32_16x16x32_bf16 v[184:187], v[224:227], v[144:147], v[184:187]
	ds_read_b128 v[216:219], v2 offset:50176
	s_waitcnt lgkmcnt(4)
	v_mfma_f32_16x16x32_bf16 v[172:175], v[228:231], v[148:151], v[172:175]
	ds_read_b128 v[220:223], v2 offset:52224
	s_waitcnt lgkmcnt(4)
	v_mfma_f32_16x16x32_bf16 v[176:179], v[232:235], v[148:151], v[176:179]
	ds_read_b128 v[224:227], v2 offset:54272
	s_waitcnt lgkmcnt(4)
	v_mfma_f32_16x16x32_bf16 v[180:183], v[236:239], v[148:151], v[180:183]
	ds_read_b128 v[228:231], v2 offset:56320
	s_waitcnt lgkmcnt(4)
	v_mfma_f32_16x16x32_bf16 v[184:187], v[212:215], v[148:151], v[184:187]
	ds_read_b128 v[232:235], v2 offset:32768
	s_waitcnt lgkmcnt(4)
	v_mfma_f32_16x16x32_bf16 v[172:175], v[216:219], v[152:155], v[172:175]
	ds_read_b128 v[236:239], v2 offset:34816
	s_waitcnt lgkmcnt(4)
	v_mfma_f32_16x16x32_bf16 v[176:179], v[220:223], v[152:155], v[176:179]
	ds_read_b128 v[212:215], v2 offset:36864
	s_waitcnt lgkmcnt(4)
	v_mfma_f32_16x16x32_bf16 v[180:183], v[224:227], v[152:155], v[180:183]
	ds_read_b128 v[216:219], v2 offset:38912
	s_waitcnt lgkmcnt(4)
	v_mfma_f32_16x16x32_bf16 v[184:187], v[228:231], v[152:155], v[184:187]
	ds_read_b128 v[220:223], v2 offset:40960
	s_waitcnt lgkmcnt(4)
	v_mfma_f32_16x16x32_bf16 v[16:19], v[232:235], v[148:151], v[16:19]
	ds_read_b128 v[224:227], v2 offset:43008
	s_waitcnt lgkmcnt(4)
	v_mfma_f32_16x16x32_bf16 v[4:7], v[236:239], v[148:151], v[4:7]
	ds_read_b128 v[228:231], v2 offset:45056
	v_bfe_u32 v156, v172, 16, 1
	v_add3_u32 v156, v172, v156, s43
	global_store_short_d16_hi v197, v156, s[86:87]
	v_bfe_u32 v157, v173, 16, 1
	v_add3_u32 v157, v173, v157, s43
	v_add_u32_e32 v189, 0x1c00, v197
	global_store_short_d16_hi v189, v157, s[86:87]
	s_waitcnt lgkmcnt(4)
	v_mfma_f32_16x16x32_bf16 v[44:47], v[212:215], v[148:151], v[44:47]
	ds_read_b128 v[232:235], v2 offset:47104
	v_bfe_u32 v158, v174, 16, 1
	v_add3_u32 v158, v174, v158, s43
	v_add_u32_e32 v190, 0x3800, v197
	global_store_short_d16_hi v190, v158, s[86:87]
	v_bfe_u32 v159, v175, 16, 1
	v_add3_u32 v159, v175, v159, s43
	v_add_u32_e32 v191, 0x5400, v197
	global_store_short_d16_hi v191, v159, s[86:87]
	s_waitcnt lgkmcnt(4)
	v_mfma_f32_16x16x32_bf16 v[76:79], v[216:219], v[148:151], v[76:79]
	ds_read_b128 v[236:239], v2 offset:33792
	s_waitcnt lgkmcnt(4)
	v_mfma_f32_16x16x32_bf16 v[84:87], v[220:223], v[148:151], v[84:87]
	ds_read_b128 v[212:215], v2 offset:35840
	v_bfe_u32 v160, v176, 16, 1
	v_add3_u32 v160, v176, v160, s43
	v_add_u32_e32 v192, 0x1c000, v197
	global_store_short_d16_hi v192, v160, s[86:87]
	v_bfe_u32 v161, v177, 16, 1
	v_add3_u32 v161, v177, v161, s43
	v_add_u32_e32 v193, 0x1dc00, v197
	global_store_short_d16_hi v193, v161, s[86:87]
	s_waitcnt lgkmcnt(4)
	v_mfma_f32_16x16x32_bf16 v[88:91], v[224:227], v[148:151], v[88:91]
	ds_read_b128 v[216:219], v2 offset:37888
	v_bfe_u32 v162, v178, 16, 1
	v_add3_u32 v162, v178, v162, s43
	v_add_u32_e32 v194, 0x1f800, v197
	global_store_short_d16_hi v194, v162, s[86:87]
	v_bfe_u32 v163, v179, 16, 1
	v_add3_u32 v163, v179, v163, s43
	v_add_u32_e32 v195, 0x21400, v197
	global_store_short_d16_hi v195, v163, s[86:87]
	s_waitcnt lgkmcnt(4)
	v_mfma_f32_16x16x32_bf16 v[92:95], v[228:231], v[148:151], v[92:95]
	ds_read_b128 v[220:223], v2 offset:39936
	s_waitcnt lgkmcnt(4)
	v_mfma_f32_16x16x32_bf16 v[96:99], v[232:235], v[148:151], v[96:99]
	ds_read_b128 v[224:227], v2 offset:41984
	v_bfe_u32 v156, v180, 16, 1
	v_add3_u32 v156, v180, v156, s43
	v_add_u32_e32 v188, 0x38000, v197
	global_store_short_d16_hi v188, v156, s[86:87]
	v_bfe_u32 v157, v181, 16, 1
	v_add3_u32 v157, v181, v157, s43
	v_add_u32_e32 v189, 0x39c00, v197
	global_store_short_d16_hi v189, v157, s[86:87]
	s_waitcnt lgkmcnt(4)
	v_mfma_f32_16x16x32_bf16 v[16:19], v[236:239], v[152:155], v[16:19]
	ds_read_b128 v[228:231], v2 offset:44032
	v_bfe_u32 v158, v182, 16, 1
	v_add3_u32 v158, v182, v158, s43
	v_add_u32_e32 v190, 0x3b800, v197
	global_store_short_d16_hi v190, v158, s[86:87]
	v_bfe_u32 v159, v183, 16, 1
	v_add3_u32 v159, v183, v159, s43
	v_add_u32_e32 v191, 0x3d400, v197
	global_store_short_d16_hi v191, v159, s[86:87]
	s_waitcnt lgkmcnt(4)
	v_mfma_f32_16x16x32_bf16 v[4:7], v[212:215], v[152:155], v[4:7]
	ds_read_b128 v[232:235], v2 offset:46080
	s_waitcnt lgkmcnt(4)
	v_mfma_f32_16x16x32_bf16 v[44:47], v[216:219], v[152:155], v[44:47]
	ds_read_b128 v[236:239], v2 offset:48128
	v_bfe_u32 v160, v184, 16, 1
	v_add3_u32 v160, v184, v160, s43
	v_add_u32_e32 v192, 0x54000, v197
	global_store_short_d16_hi v192, v160, s[86:87]
	v_bfe_u32 v161, v185, 16, 1
	v_add3_u32 v161, v185, v161, s43
	v_add_u32_e32 v193, 0x55c00, v197
	global_store_short_d16_hi v193, v161, s[86:87]
	s_waitcnt lgkmcnt(4)
	v_mfma_f32_16x16x32_bf16 v[76:79], v[220:223], v[152:155], v[76:79]
	v_bfe_u32 v162, v186, 16, 1
	v_add3_u32 v162, v186, v162, s43
	v_add_u32_e32 v194, 0x57800, v197
	global_store_short_d16_hi v194, v162, s[86:87]
	v_bfe_u32 v163, v187, 16, 1
	v_add3_u32 v163, v187, v163, s43
	v_add_u32_e32 v195, 0x59400, v197
	global_store_short_d16_hi v195, v163, s[86:87]
	s_waitcnt lgkmcnt(3)
	v_mfma_f32_16x16x32_bf16 v[84:87], v[224:227], v[152:155], v[84:87]
	s_waitcnt lgkmcnt(2)
	v_mfma_f32_16x16x32_bf16 v[88:91], v[228:231], v[152:155], v[88:91]
	s_waitcnt lgkmcnt(1)
	v_mfma_f32_16x16x32_bf16 v[92:95], v[232:235], v[152:155], v[92:95]
	s_waitcnt lgkmcnt(0)
	v_mfma_f32_16x16x32_bf16 v[96:99], v[236:239], v[152:155], v[96:99]
	s_andn2_b64 vcc, exec, s[4:5]
	s_waitcnt lgkmcnt(0)
	s_barrier
	s_cbranch_vccnz .LBB0_489
	s_waitcnt vmcnt(0)
	ds_write_b128 v1, v[8:11]
	ds_write_b128 v1, v[48:51] offset:32768
	ds_write_b128 v124, v[12:15]
	ds_write_b128 v124, v[52:55] offset:32768
	ds_write_b128 v125, v[20:23]
	ds_write_b128 v125, v[56:59] offset:32768
	ds_write_b128 v126, v[24:27]
	ds_write_b128 v126, v[60:63] offset:32768
	ds_write_b128 v127, v[28:31]
	ds_write_b128 v127, v[64:67] offset:32768
	ds_write_b128 v128, v[32:35]
	ds_write_b128 v128, v[68:71] offset:32768
	ds_write_b128 v129, v[36:39]
	ds_write_b128 v129, v[72:75] offset:32768
	ds_write_b128 v130, v[40:43]
	ds_write_b128 v130, v[80:83] offset:32768
	s_branch .LBB0_489
